# GEMM units: first K-iteration peeled in the four full main-loop instances, first MFMA per accumulator takes C=0, the 127 accumulator-zeroing moves per unit are gone
# speedup vs baseline: 1.0056x; 1.0056x over previous
.LBB0_342:
	s_and_b64 s[10:11], s[48:49], exec
	s_cselect_b32 s50, s45, s5
	s_cselect_b32 s51, s44, s4
	s_cselect_b32 s53, s47, s9
	s_cselect_b32 s54, s46, s8
	s_add_u32 s55, s8, 0x100
	s_addc_u32 s78, s9, 0
	s_add_u32 s4, s4, 0x40080
	v_mov_b32_e32 v0, 0
	s_addc_u32 s5, s5, 0
	s_mov_b32 s79, -2
	ds_read_b128 v[128:131], v169
	ds_read_b128 v[132:135], v169 offset:1024
	ds_read_b128 v[136:139], v169 offset:2048
	ds_read_b128 v[140:143], v169 offset:3072
	ds_read_b128 v[158:161], v170
	ds_read_b128 v[162:165], v170 offset:1024
	ds_read_b128 v[178:181], v170 offset:2048
	ds_read_b128 v[182:185], v170 offset:3072
	s_add_u32 s8, s4, 0xfffc0080
	s_addc_u32 s9, s5, -1
	s_cmp_eq_u32 s79, 12
	s_cselect_b32 s11, s50, s9
	s_cselect_b32 s10, s51, s8
	s_cselect_b32 s9, s53, s78
	s_cselect_b32 s8, s54, s55
	v_lshl_add_u64 v[218:219], s[4:5], 0, v[156:157]
	s_add_i32 m0, s28, 0xc000
	ds_read_b128 v[186:189], v171
	ds_read_b128 v[190:193], v171 offset:1024
	ds_read_b128 v[194:197], v171 offset:2048
	ds_read_b128 v[198:201], v171 offset:3072
	ds_read_b128 v[202:205], v171 offset:4096
	ds_read_b128 v[206:209], v171 offset:5120
	ds_read_b128 v[210:213], v171 offset:6144
	ds_read_b128 v[214:217], v171 offset:7168
	global_load_lds_dwordx4 v[218:219], off
	v_lshl_add_u64 v[218:219], s[4:5], 0, v[154:155]
	s_add_i32 m0, s28, 0xe000
	s_nop 0
	global_load_lds_dwordx4 v[218:219], off
	s_waitcnt vmcnt(8)
	s_waitcnt lgkmcnt(0)
	s_barrier
	s_setprio 1
	s_waitcnt lgkmcnt(0)
	v_mfma_f32_16x16x32_bf16 v[124:127], v[128:131], v[186:189], 0
	v_mfma_f32_16x16x32_bf16 v[120:123], v[136:139], v[186:189], 0
	v_mfma_f32_16x16x32_bf16 v[108:111], v[128:131], v[194:197], 0
	v_mfma_f32_16x16x32_bf16 v[104:107], v[136:139], v[194:197], 0
	v_mfma_f32_16x16x32_bf16 v[92:95], v[128:131], v[202:205], 0
	v_mfma_f32_16x16x32_bf16 v[88:91], v[136:139], v[202:205], 0
	v_mfma_f32_16x16x32_bf16 v[76:79], v[128:131], v[210:213], 0
	v_mfma_f32_16x16x32_bf16 v[72:75], v[136:139], v[210:213], 0
	v_mfma_f32_16x16x32_bf16 v[124:127], v[132:135], v[190:193], v[124:127]
	v_mfma_f32_16x16x32_bf16 v[120:123], v[140:143], v[190:193], v[120:123]
	v_mfma_f32_16x16x32_bf16 v[108:111], v[132:135], v[198:201], v[108:111]
	v_mfma_f32_16x16x32_bf16 v[104:107], v[140:143], v[198:201], v[104:107]
	v_mfma_f32_16x16x32_bf16 v[92:95], v[132:135], v[206:209], v[92:95]
	v_mfma_f32_16x16x32_bf16 v[88:91], v[140:143], v[206:209], v[88:91]
	v_mfma_f32_16x16x32_bf16 v[76:79], v[132:135], v[214:217], v[76:79]
	v_mfma_f32_16x16x32_bf16 v[72:75], v[140:143], v[214:217], v[72:75]
	s_setprio 0
	s_setprio 1
	v_mfma_f32_16x16x32_bf16 v[116:119], v[158:161], v[186:189], 0
	v_mfma_f32_16x16x32_bf16 v[112:115], v[178:181], v[186:189], 0
	v_mfma_f32_16x16x32_bf16 v[100:103], v[158:161], v[194:197], 0
	v_mfma_f32_16x16x32_bf16 v[96:99], v[178:181], v[194:197], 0
	v_mfma_f32_16x16x32_bf16 v[84:87], v[158:161], v[202:205], 0
	v_mfma_f32_16x16x32_bf16 v[80:83], v[178:181], v[202:205], 0
	v_mfma_f32_16x16x32_bf16 v[68:71], v[158:161], v[210:213], 0
	v_mfma_f32_16x16x32_bf16 v[64:67], v[178:181], v[210:213], 0
	v_mfma_f32_16x16x32_bf16 v[116:119], v[162:165], v[190:193], v[116:119]
	v_mfma_f32_16x16x32_bf16 v[112:115], v[182:185], v[190:193], v[112:115]
	v_mfma_f32_16x16x32_bf16 v[100:103], v[162:165], v[198:201], v[100:103]
	v_mfma_f32_16x16x32_bf16 v[96:99], v[182:185], v[198:201], v[96:99]
	v_mfma_f32_16x16x32_bf16 v[84:87], v[162:165], v[206:209], v[84:87]
	v_mfma_f32_16x16x32_bf16 v[80:83], v[182:185], v[206:209], v[80:83]
	v_mfma_f32_16x16x32_bf16 v[68:71], v[162:165], v[214:217], v[68:71]
	v_mfma_f32_16x16x32_bf16 v[64:67], v[182:185], v[214:217], v[64:67]
	s_setprio 0
	s_barrier
	s_add_i32 s26, s63, s13
	v_lshl_add_u64 v[218:219], s[8:9], 0, v[146:147]
	s_mov_b32 m0, s26
	ds_read_b128 v[186:189], v171 offset:16384
	ds_read_b128 v[190:193], v171 offset:17408
	ds_read_b128 v[194:197], v171 offset:18432
	ds_read_b128 v[198:201], v171 offset:19456
	ds_read_b128 v[202:205], v171 offset:20480
	ds_read_b128 v[206:209], v171 offset:21504
	ds_read_b128 v[210:213], v171 offset:22528
	ds_read_b128 v[214:217], v171 offset:23552
	global_load_lds_dwordx4 v[218:219], off
	s_add_i32 m0, s26, 0x2000
	s_add_u32 s26, s8, 0x40000
	v_lshl_add_u64 v[220:221], s[8:9], 0, v[150:151]
	s_addc_u32 s27, s9, 0
	s_add_i32 s77, s64, s13
	global_load_lds_dwordx4 v[220:221], off
	v_lshl_add_u64 v[222:223], s[26:27], 0, v[146:147]
	s_mov_b32 m0, s77
	v_lshl_add_u64 v[224:225], s[10:11], 0, v[148:149]
	global_load_lds_dwordx4 v[222:223], off
	v_lshl_add_u64 v[222:223], s[26:27], 0, v[150:151]
	s_add_i32 m0, s77, 0x2000
	s_nop 0
	global_load_lds_dwordx4 v[222:223], off
	v_lshl_add_u64 v[222:223], s[10:11], 0, v[144:145]
	s_mov_b32 m0, s28
	s_nop 0
	global_load_lds_dwordx4 v[222:223], off
	s_mov_b32 m0, s29
	s_nop 0
	global_load_lds_dwordx4 v[224:225], off
	s_waitcnt vmcnt(8)
	s_waitcnt lgkmcnt(0)
	s_barrier
	s_setprio 1
	s_waitcnt lgkmcnt(0)
	v_mfma_f32_16x16x32_bf16 v[60:63], v[128:131], v[186:189], 0
	v_mfma_f32_16x16x32_bf16 v[56:59], v[136:139], v[186:189], 0
	v_mfma_f32_16x16x32_bf16 v[44:47], v[128:131], v[194:197], 0
	v_mfma_f32_16x16x32_bf16 v[40:43], v[136:139], v[194:197], 0
	v_mfma_f32_16x16x32_bf16 v[28:31], v[128:131], v[202:205], 0
	v_mfma_f32_16x16x32_bf16 v[24:27], v[136:139], v[202:205], 0
	v_mfma_f32_16x16x32_bf16 v[12:15], v[128:131], v[210:213], 0
	v_mfma_f32_16x16x32_bf16 v[8:11], v[136:139], v[210:213], 0
	v_mfma_f32_16x16x32_bf16 v[60:63], v[132:135], v[190:193], v[60:63]
	v_mfma_f32_16x16x32_bf16 v[56:59], v[140:143], v[190:193], v[56:59]
	v_mfma_f32_16x16x32_bf16 v[44:47], v[132:135], v[198:201], v[44:47]
	v_mfma_f32_16x16x32_bf16 v[40:43], v[140:143], v[198:201], v[40:43]
	v_mfma_f32_16x16x32_bf16 v[28:31], v[132:135], v[206:209], v[28:31]
	v_mfma_f32_16x16x32_bf16 v[24:27], v[140:143], v[206:209], v[24:27]
	v_mfma_f32_16x16x32_bf16 v[12:15], v[132:135], v[214:217], v[12:15]
	v_mfma_f32_16x16x32_bf16 v[8:11], v[140:143], v[214:217], v[8:11]
	s_setprio 0
	s_setprio 1
	v_mfma_f32_16x16x32_bf16 v[52:55], v[158:161], v[186:189], 0
	v_mfma_f32_16x16x32_bf16 v[48:51], v[178:181], v[186:189], 0
	v_mfma_f32_16x16x32_bf16 v[36:39], v[158:161], v[194:197], 0
	v_mfma_f32_16x16x32_bf16 v[32:35], v[178:181], v[194:197], 0
	v_mfma_f32_16x16x32_bf16 v[20:23], v[158:161], v[202:205], 0
	v_mfma_f32_16x16x32_bf16 v[16:19], v[178:181], v[202:205], 0
	v_mfma_f32_16x16x32_bf16 v[4:7], v[158:161], v[210:213], 0
	v_mfma_f32_16x16x32_bf16 v[0:3], v[178:181], v[210:213], 0
	v_mfma_f32_16x16x32_bf16 v[52:55], v[162:165], v[190:193], v[52:55]
	v_mfma_f32_16x16x32_bf16 v[48:51], v[182:185], v[190:193], v[48:51]
	v_mfma_f32_16x16x32_bf16 v[36:39], v[162:165], v[198:201], v[36:39]
	v_mfma_f32_16x16x32_bf16 v[32:35], v[182:185], v[198:201], v[32:35]
	v_mfma_f32_16x16x32_bf16 v[20:23], v[162:165], v[206:209], v[20:23]
	v_mfma_f32_16x16x32_bf16 v[16:19], v[182:185], v[206:209], v[16:19]
	v_mfma_f32_16x16x32_bf16 v[4:7], v[162:165], v[214:217], v[4:7]
	v_mfma_f32_16x16x32_bf16 v[0:3], v[182:185], v[214:217], v[0:3]
	s_setprio 0
	s_barrier
	s_add_i32 s26, 0, 0x18000
	s_add_i32 s27, 0, 0x1c000
	v_add_u32_e32 v140, s26, v168
	v_add_u32_e32 v152, s27, v168
	ds_read_b128 v[128:131], v140
	ds_read_b128 v[132:135], v140 offset:1024
	ds_read_b128 v[136:139], v140 offset:2048
	ds_read_b128 v[140:143], v140 offset:3072
	ds_read_b128 v[158:161], v152
	ds_read_b128 v[162:165], v152 offset:1024
	ds_read_b128 v[178:181], v152 offset:2048
	ds_read_b128 v[182:185], v152 offset:3072
	s_add_u32 s10, s10, 0x40000
	s_addc_u32 s11, s11, 0
	s_mov_b32 m0, s56
	v_lshl_add_u64 v[226:227], s[10:11], 0, v[144:145]
	ds_read_b128 v[186:189], v171 offset:32768
	ds_read_b128 v[190:193], v171 offset:33792
	ds_read_b128 v[194:197], v171 offset:34816
	ds_read_b128 v[198:201], v171 offset:35840
	ds_read_b128 v[202:205], v171 offset:36864
	ds_read_b128 v[206:209], v171 offset:37888
	ds_read_b128 v[210:213], v171 offset:38912
	ds_read_b128 v[214:217], v171 offset:39936
	global_load_lds_dwordx4 v[226:227], off
	v_lshl_add_u64 v[226:227], s[10:11], 0, v[148:149]
	s_mov_b32 m0, s57
	s_nop 0
	global_load_lds_dwordx4 v[226:227], off
	s_waitcnt vmcnt(8)
	s_waitcnt lgkmcnt(0)
	s_barrier
	s_setprio 1
	s_waitcnt lgkmcnt(0)
	v_mfma_f32_16x16x32_bf16 v[124:127], v[128:131], v[186:189], v[124:127]
	v_mfma_f32_16x16x32_bf16 v[120:123], v[136:139], v[186:189], v[120:123]
	v_mfma_f32_16x16x32_bf16 v[108:111], v[128:131], v[194:197], v[108:111]
	v_mfma_f32_16x16x32_bf16 v[104:107], v[136:139], v[194:197], v[104:107]
	v_mfma_f32_16x16x32_bf16 v[92:95], v[128:131], v[202:205], v[92:95]
	v_mfma_f32_16x16x32_bf16 v[88:91], v[136:139], v[202:205], v[88:91]
	v_mfma_f32_16x16x32_bf16 v[76:79], v[128:131], v[210:213], v[76:79]
	v_mfma_f32_16x16x32_bf16 v[72:75], v[136:139], v[210:213], v[72:75]
	v_mfma_f32_16x16x32_bf16 v[124:127], v[132:135], v[190:193], v[124:127]
	v_mfma_f32_16x16x32_bf16 v[120:123], v[140:143], v[190:193], v[120:123]
	v_mfma_f32_16x16x32_bf16 v[108:111], v[132:135], v[198:201], v[108:111]
	v_mfma_f32_16x16x32_bf16 v[104:107], v[140:143], v[198:201], v[104:107]
	v_mfma_f32_16x16x32_bf16 v[92:95], v[132:135], v[206:209], v[92:95]
	v_mfma_f32_16x16x32_bf16 v[88:91], v[140:143], v[206:209], v[88:91]
	v_mfma_f32_16x16x32_bf16 v[76:79], v[132:135], v[214:217], v[76:79]
	v_mfma_f32_16x16x32_bf16 v[72:75], v[140:143], v[214:217], v[72:75]
	s_setprio 0
	s_setprio 1
	v_mfma_f32_16x16x32_bf16 v[116:119], v[158:161], v[186:189], v[116:119]
	v_mfma_f32_16x16x32_bf16 v[112:115], v[178:181], v[186:189], v[112:115]
	v_mfma_f32_16x16x32_bf16 v[100:103], v[158:161], v[194:197], v[100:103]
	v_mfma_f32_16x16x32_bf16 v[96:99], v[178:181], v[194:197], v[96:99]
	v_mfma_f32_16x16x32_bf16 v[84:87], v[158:161], v[202:205], v[84:87]
	v_mfma_f32_16x16x32_bf16 v[80:83], v[178:181], v[202:205], v[80:83]
	v_mfma_f32_16x16x32_bf16 v[68:71], v[158:161], v[210:213], v[68:71]
	v_mfma_f32_16x16x32_bf16 v[64:67], v[178:181], v[210:213], v[64:67]
	v_mfma_f32_16x16x32_bf16 v[116:119], v[162:165], v[190:193], v[116:119]
	v_mfma_f32_16x16x32_bf16 v[112:115], v[182:185], v[190:193], v[112:115]
	v_mfma_f32_16x16x32_bf16 v[100:103], v[162:165], v[198:201], v[100:103]
	v_mfma_f32_16x16x32_bf16 v[96:99], v[182:185], v[198:201], v[96:99]
	v_mfma_f32_16x16x32_bf16 v[84:87], v[162:165], v[206:209], v[84:87]
	v_mfma_f32_16x16x32_bf16 v[80:83], v[182:185], v[206:209], v[80:83]
	v_mfma_f32_16x16x32_bf16 v[68:71], v[162:165], v[214:217], v[68:71]
	v_mfma_f32_16x16x32_bf16 v[64:67], v[182:185], v[214:217], v[64:67]
	s_setprio 0
	s_barrier
	s_add_i32 s10, s26, s13
	v_lshl_add_u64 v[218:219], v[218:219], 0, s[34:35]
	s_mov_b32 m0, s10
	ds_read_b128 v[186:189], v171 offset:49152
	ds_read_b128 v[190:193], v171 offset:50176
	ds_read_b128 v[194:197], v171 offset:51200
	ds_read_b128 v[198:201], v171 offset:52224
	ds_read_b128 v[202:205], v171 offset:53248
	ds_read_b128 v[206:209], v171 offset:54272
	ds_read_b128 v[210:213], v171 offset:55296
	ds_read_b128 v[214:217], v171 offset:56320
	global_load_lds_dwordx4 v[218:219], off
	s_add_i32 m0, s10, 0x2000
	s_add_u32 s8, s8, 0x40080
	v_lshl_add_u64 v[218:219], v[220:221], 0, s[34:35]
	s_addc_u32 s9, s9, 0
	s_add_i32 s10, s27, s13
	global_load_lds_dwordx4 v[218:219], off
	v_lshl_add_u64 v[218:219], s[8:9], 0, v[146:147]
	s_mov_b32 m0, s10
	s_nop 0
	global_load_lds_dwordx4 v[218:219], off
	v_lshl_add_u64 v[218:219], s[8:9], 0, v[150:151]
	s_add_i32 m0, s10, 0x2000
	s_nop 0
	global_load_lds_dwordx4 v[218:219], off
	v_lshl_add_u64 v[218:219], v[222:223], 0, s[34:35]
	s_mov_b32 m0, s61
	s_nop 0
	global_load_lds_dwordx4 v[218:219], off
	v_lshl_add_u64 v[218:219], v[224:225], 0, s[34:35]
	s_mov_b32 m0, s62
	s_nop 0
	global_load_lds_dwordx4 v[218:219], off
	s_waitcnt vmcnt(8)
	s_waitcnt lgkmcnt(0)
	s_barrier
	s_setprio 1
	s_waitcnt lgkmcnt(0)
	v_mfma_f32_16x16x32_bf16 v[60:63], v[128:131], v[186:189], v[60:63]
	v_mfma_f32_16x16x32_bf16 v[56:59], v[136:139], v[186:189], v[56:59]
	v_mfma_f32_16x16x32_bf16 v[44:47], v[128:131], v[194:197], v[44:47]
	v_mfma_f32_16x16x32_bf16 v[40:43], v[136:139], v[194:197], v[40:43]
	v_mfma_f32_16x16x32_bf16 v[28:31], v[128:131], v[202:205], v[28:31]
	v_mfma_f32_16x16x32_bf16 v[24:27], v[136:139], v[202:205], v[24:27]
	v_mfma_f32_16x16x32_bf16 v[12:15], v[128:131], v[210:213], v[12:15]
	v_mfma_f32_16x16x32_bf16 v[8:11], v[136:139], v[210:213], v[8:11]
	v_mfma_f32_16x16x32_bf16 v[60:63], v[132:135], v[190:193], v[60:63]
	v_mfma_f32_16x16x32_bf16 v[56:59], v[140:143], v[190:193], v[56:59]
	v_mfma_f32_16x16x32_bf16 v[44:47], v[132:135], v[198:201], v[44:47]
	v_mfma_f32_16x16x32_bf16 v[40:43], v[140:143], v[198:201], v[40:43]
	v_mfma_f32_16x16x32_bf16 v[28:31], v[132:135], v[206:209], v[28:31]
	v_mfma_f32_16x16x32_bf16 v[24:27], v[140:143], v[206:209], v[24:27]
	v_mfma_f32_16x16x32_bf16 v[12:15], v[132:135], v[214:217], v[12:15]
	v_mfma_f32_16x16x32_bf16 v[8:11], v[140:143], v[214:217], v[8:11]
	s_setprio 0
	s_setprio 1
	v_mfma_f32_16x16x32_bf16 v[52:55], v[158:161], v[186:189], v[52:55]
	v_mfma_f32_16x16x32_bf16 v[48:51], v[178:181], v[186:189], v[48:51]
	v_mfma_f32_16x16x32_bf16 v[36:39], v[158:161], v[194:197], v[36:39]
	v_mfma_f32_16x16x32_bf16 v[32:35], v[178:181], v[194:197], v[32:35]
	v_mfma_f32_16x16x32_bf16 v[20:23], v[158:161], v[202:205], v[20:23]
	v_mfma_f32_16x16x32_bf16 v[16:19], v[178:181], v[202:205], v[16:19]
	v_mfma_f32_16x16x32_bf16 v[4:7], v[158:161], v[210:213], v[4:7]
	v_mfma_f32_16x16x32_bf16 v[0:3], v[178:181], v[210:213], v[0:3]
	v_mfma_f32_16x16x32_bf16 v[52:55], v[162:165], v[190:193], v[52:55]
	v_mfma_f32_16x16x32_bf16 v[48:51], v[182:185], v[190:193], v[48:51]
	v_mfma_f32_16x16x32_bf16 v[36:39], v[162:165], v[198:201], v[36:39]
	v_mfma_f32_16x16x32_bf16 v[32:35], v[182:185], v[198:201], v[32:35]
	v_mfma_f32_16x16x32_bf16 v[20:23], v[162:165], v[206:209], v[20:23]
	v_mfma_f32_16x16x32_bf16 v[16:19], v[182:185], v[206:209], v[16:19]
	v_mfma_f32_16x16x32_bf16 v[4:7], v[162:165], v[214:217], v[4:7]
	v_mfma_f32_16x16x32_bf16 v[0:3], v[182:185], v[214:217], v[0:3]
	s_setprio 0
	s_barrier
	s_add_i32 s79, s79, 2
	s_add_u32 s55, s55, 0x100
	s_addc_u32 s78, s78, 0
	s_add_u32 s4, s4, 0x100
	s_addc_u32 s5, s5, 0

.LBB0_818:
	s_add_u32 s5, s70, 0x100
	s_addc_u32 s61, s71, 0
	s_add_u32 s68, s68, 0x40080
	v_mov_b32_e32 v0, 0
	s_addc_u32 s69, s69, 0
	s_mov_b32 s91, -2
	s_waitcnt lgkmcnt(0)
	ds_read_b128 v[104:107], v229
	ds_read_b128 v[108:111], v229 offset:1024
	ds_read_b128 v[128:131], v229 offset:2048
	ds_read_b128 v[132:135], v229 offset:3072
	ds_read_b128 v[144:147], v230
	ds_read_b128 v[148:151], v230 offset:1024
	ds_read_b128 v[152:155], v230 offset:2048
	ds_read_b128 v[156:159], v230 offset:3072
	s_add_u32 s26, s68, 0xfffc0080
	s_addc_u32 s27, s69, -1
	s_cmp_eq_u32 s91, 12
	s_cselect_b32 s73, s63, s27
	s_cselect_b32 s72, s62, s26
	s_cselect_b32 s71, s65, s61
	s_cselect_b32 s70, s64, s5
	v_lshl_add_u64 v[204:205], s[68:69], 0, v[202:203]
	s_add_i32 m0, s28, 0xc000
	ds_read_b128 v[160:163], v231
	ds_read_b128 v[164:167], v231 offset:1024
	ds_read_b128 v[168:171], v231 offset:2048
	ds_read_b128 v[172:175], v231 offset:3072
	ds_read_b128 v[176:179], v231 offset:4096
	ds_read_b128 v[180:183], v231 offset:5120
	ds_read_b128 v[184:187], v231 offset:6144
	ds_read_b128 v[188:191], v231 offset:7168
	global_load_lds_dwordx4 v[204:205], off
	v_lshl_add_u64 v[204:205], s[68:69], 0, v[200:201]
	s_add_i32 m0, s28, 0xe000
	s_nop 0
	global_load_lds_dwordx4 v[204:205], off
	s_waitcnt vmcnt(8)
	s_waitcnt lgkmcnt(0)
	s_barrier
	s_setprio 1
	s_waitcnt lgkmcnt(0)
	v_mfma_f32_16x16x32_bf16 v[140:143], v[104:107], v[160:163], 0
	v_mfma_f32_16x16x32_bf16 v[136:139], v[128:131], v[160:163], 0
	v_mfma_f32_16x16x32_bf16 v[116:119], v[104:107], v[168:171], 0
	v_mfma_f32_16x16x32_bf16 v[112:115], v[128:131], v[168:171], 0
	v_mfma_f32_16x16x32_bf16 v[92:95], v[104:107], v[176:179], 0
	v_mfma_f32_16x16x32_bf16 v[88:91], v[128:131], v[176:179], 0
	v_mfma_f32_16x16x32_bf16 v[76:79], v[104:107], v[184:187], 0
	v_mfma_f32_16x16x32_bf16 v[72:75], v[128:131], v[184:187], 0
	v_mfma_f32_16x16x32_bf16 v[140:143], v[108:111], v[164:167], v[140:143]
	v_mfma_f32_16x16x32_bf16 v[136:139], v[132:135], v[164:167], v[136:139]
	v_mfma_f32_16x16x32_bf16 v[116:119], v[108:111], v[172:175], v[116:119]
	v_mfma_f32_16x16x32_bf16 v[112:115], v[132:135], v[172:175], v[112:115]
	v_mfma_f32_16x16x32_bf16 v[92:95], v[108:111], v[180:183], v[92:95]
	v_mfma_f32_16x16x32_bf16 v[88:91], v[132:135], v[180:183], v[88:91]
	v_mfma_f32_16x16x32_bf16 v[76:79], v[108:111], v[188:191], v[76:79]
	v_mfma_f32_16x16x32_bf16 v[72:75], v[132:135], v[188:191], v[72:75]
	s_setprio 0
	s_setprio 1
	v_mfma_f32_16x16x32_bf16 v[124:127], v[144:147], v[160:163], 0
	v_mfma_f32_16x16x32_bf16 v[120:123], v[152:155], v[160:163], 0
	v_mfma_f32_16x16x32_bf16 v[100:103], v[144:147], v[168:171], 0
	v_mfma_f32_16x16x32_bf16 v[96:99], v[152:155], v[168:171], 0
	v_mfma_f32_16x16x32_bf16 v[84:87], v[144:147], v[176:179], 0
	v_mfma_f32_16x16x32_bf16 v[80:83], v[152:155], v[176:179], 0
	v_mfma_f32_16x16x32_bf16 v[68:71], v[144:147], v[184:187], 0
	v_mfma_f32_16x16x32_bf16 v[64:67], v[152:155], v[184:187], 0
	v_mfma_f32_16x16x32_bf16 v[124:127], v[148:151], v[164:167], v[124:127]
	v_mfma_f32_16x16x32_bf16 v[120:123], v[156:159], v[164:167], v[120:123]
	v_mfma_f32_16x16x32_bf16 v[100:103], v[148:151], v[172:175], v[100:103]
	v_mfma_f32_16x16x32_bf16 v[96:99], v[156:159], v[172:175], v[96:99]
	v_mfma_f32_16x16x32_bf16 v[84:87], v[148:151], v[180:183], v[84:87]
	v_mfma_f32_16x16x32_bf16 v[80:83], v[156:159], v[180:183], v[80:83]
	v_mfma_f32_16x16x32_bf16 v[68:71], v[148:151], v[188:191], v[68:71]
	v_mfma_f32_16x16x32_bf16 v[64:67], v[156:159], v[188:191], v[64:67]
	s_setprio 0
	s_barrier
	s_add_i32 s26, s83, s3
	v_lshl_add_u64 v[204:205], s[70:71], 0, v[194:195]
	s_mov_b32 m0, s26
	ds_read_b128 v[160:163], v231 offset:16384
	ds_read_b128 v[164:167], v231 offset:17408
	ds_read_b128 v[168:171], v231 offset:18432
	ds_read_b128 v[172:175], v231 offset:19456
	ds_read_b128 v[176:179], v231 offset:20480
	ds_read_b128 v[180:183], v231 offset:21504
	ds_read_b128 v[184:187], v231 offset:22528
	ds_read_b128 v[188:191], v231 offset:23552
	global_load_lds_dwordx4 v[204:205], off
	s_add_i32 m0, s26, 0x2000
	s_add_u32 s26, s70, 0x40000
	v_lshl_add_u64 v[206:207], s[70:71], 0, v[198:199]
	s_addc_u32 s27, s71, 0
	s_add_i32 s77, s84, s3
	global_load_lds_dwordx4 v[206:207], off
	v_lshl_add_u64 v[208:209], s[26:27], 0, v[194:195]
	s_mov_b32 m0, s77
	v_lshl_add_u64 v[210:211], s[72:73], 0, v[196:197]
	global_load_lds_dwordx4 v[208:209], off
	v_lshl_add_u64 v[208:209], s[26:27], 0, v[198:199]
	s_add_i32 m0, s77, 0x2000
	s_nop 0
	global_load_lds_dwordx4 v[208:209], off
	v_lshl_add_u64 v[208:209], s[72:73], 0, v[192:193]
	s_mov_b32 m0, s28
	s_nop 0
	global_load_lds_dwordx4 v[208:209], off
	s_mov_b32 m0, s29
	s_nop 0
	global_load_lds_dwordx4 v[210:211], off
	s_waitcnt vmcnt(8)
	s_waitcnt lgkmcnt(0)
	s_barrier
	s_setprio 1
	s_waitcnt lgkmcnt(0)
	v_mfma_f32_16x16x32_bf16 v[60:63], v[104:107], v[160:163], 0
	v_mfma_f32_16x16x32_bf16 v[56:59], v[128:131], v[160:163], 0
	v_mfma_f32_16x16x32_bf16 v[44:47], v[104:107], v[168:171], 0
	v_mfma_f32_16x16x32_bf16 v[40:43], v[128:131], v[168:171], 0
	v_mfma_f32_16x16x32_bf16 v[28:31], v[104:107], v[176:179], 0
	v_mfma_f32_16x16x32_bf16 v[24:27], v[128:131], v[176:179], 0
	v_mfma_f32_16x16x32_bf16 v[12:15], v[104:107], v[184:187], 0
	v_mfma_f32_16x16x32_bf16 v[8:11], v[128:131], v[184:187], 0
	v_mfma_f32_16x16x32_bf16 v[60:63], v[108:111], v[164:167], v[60:63]
	v_mfma_f32_16x16x32_bf16 v[56:59], v[132:135], v[164:167], v[56:59]
	v_mfma_f32_16x16x32_bf16 v[44:47], v[108:111], v[172:175], v[44:47]
	v_mfma_f32_16x16x32_bf16 v[40:43], v[132:135], v[172:175], v[40:43]
	v_mfma_f32_16x16x32_bf16 v[28:31], v[108:111], v[180:183], v[28:31]
	v_mfma_f32_16x16x32_bf16 v[24:27], v[132:135], v[180:183], v[24:27]
	v_mfma_f32_16x16x32_bf16 v[12:15], v[108:111], v[188:191], v[12:15]
	v_mfma_f32_16x16x32_bf16 v[8:11], v[132:135], v[188:191], v[8:11]
	s_setprio 0
	s_setprio 1
	v_mfma_f32_16x16x32_bf16 v[52:55], v[144:147], v[160:163], 0
	v_mfma_f32_16x16x32_bf16 v[48:51], v[152:155], v[160:163], 0
	v_mfma_f32_16x16x32_bf16 v[36:39], v[144:147], v[168:171], 0
	v_mfma_f32_16x16x32_bf16 v[32:35], v[152:155], v[168:171], 0
	v_mfma_f32_16x16x32_bf16 v[20:23], v[144:147], v[176:179], 0
	v_mfma_f32_16x16x32_bf16 v[16:19], v[152:155], v[176:179], 0
	v_mfma_f32_16x16x32_bf16 v[4:7], v[144:147], v[184:187], 0
	v_mfma_f32_16x16x32_bf16 v[0:3], v[152:155], v[184:187], 0
	v_mfma_f32_16x16x32_bf16 v[52:55], v[148:151], v[164:167], v[52:55]
	v_mfma_f32_16x16x32_bf16 v[48:51], v[156:159], v[164:167], v[48:51]
	v_mfma_f32_16x16x32_bf16 v[36:39], v[148:151], v[172:175], v[36:39]
	v_mfma_f32_16x16x32_bf16 v[32:35], v[156:159], v[172:175], v[32:35]
	v_mfma_f32_16x16x32_bf16 v[20:23], v[148:151], v[180:183], v[20:23]
	v_mfma_f32_16x16x32_bf16 v[16:19], v[156:159], v[180:183], v[16:19]
	v_mfma_f32_16x16x32_bf16 v[4:7], v[148:151], v[188:191], v[4:7]
	v_mfma_f32_16x16x32_bf16 v[0:3], v[156:159], v[188:191], v[0:3]
	s_setprio 0
	s_barrier
	s_add_i32 s77, 0, 0x18000
	s_add_i32 s92, 0, 0x1c000
	v_add_u32_e32 v132, s77, v228
	v_add_u32_e32 v156, s92, v228
	ds_read_b128 v[104:107], v132
	ds_read_b128 v[108:111], v132 offset:1024
	ds_read_b128 v[128:131], v132 offset:2048
	ds_read_b128 v[132:135], v132 offset:3072
	ds_read_b128 v[144:147], v156
	ds_read_b128 v[148:151], v156 offset:1024
	ds_read_b128 v[152:155], v156 offset:2048
	ds_read_b128 v[156:159], v156 offset:3072
	s_add_u32 s26, s72, 0x40000
	s_addc_u32 s27, s73, 0
	s_mov_b32 m0, s30
	v_lshl_add_u64 v[212:213], s[26:27], 0, v[192:193]
	ds_read_b128 v[160:163], v231 offset:32768
	ds_read_b128 v[164:167], v231 offset:33792
	ds_read_b128 v[168:171], v231 offset:34816
	ds_read_b128 v[172:175], v231 offset:35840
	ds_read_b128 v[176:179], v231 offset:36864
	ds_read_b128 v[180:183], v231 offset:37888
	ds_read_b128 v[184:187], v231 offset:38912
	ds_read_b128 v[188:191], v231 offset:39936
	global_load_lds_dwordx4 v[212:213], off
	v_lshl_add_u64 v[212:213], s[26:27], 0, v[196:197]
	s_mov_b32 m0, s31
	s_nop 0
	global_load_lds_dwordx4 v[212:213], off
	s_waitcnt vmcnt(8)
	s_waitcnt lgkmcnt(0)
	s_barrier
	s_setprio 1
	s_waitcnt lgkmcnt(0)
	v_mfma_f32_16x16x32_bf16 v[140:143], v[104:107], v[160:163], v[140:143]
	v_mfma_f32_16x16x32_bf16 v[136:139], v[128:131], v[160:163], v[136:139]
	v_mfma_f32_16x16x32_bf16 v[116:119], v[104:107], v[168:171], v[116:119]
	v_mfma_f32_16x16x32_bf16 v[112:115], v[128:131], v[168:171], v[112:115]
	v_mfma_f32_16x16x32_bf16 v[92:95], v[104:107], v[176:179], v[92:95]
	v_mfma_f32_16x16x32_bf16 v[88:91], v[128:131], v[176:179], v[88:91]
	v_mfma_f32_16x16x32_bf16 v[76:79], v[104:107], v[184:187], v[76:79]
	v_mfma_f32_16x16x32_bf16 v[72:75], v[128:131], v[184:187], v[72:75]
	v_mfma_f32_16x16x32_bf16 v[140:143], v[108:111], v[164:167], v[140:143]
	v_mfma_f32_16x16x32_bf16 v[136:139], v[132:135], v[164:167], v[136:139]
	v_mfma_f32_16x16x32_bf16 v[116:119], v[108:111], v[172:175], v[116:119]
	v_mfma_f32_16x16x32_bf16 v[112:115], v[132:135], v[172:175], v[112:115]
	v_mfma_f32_16x16x32_bf16 v[92:95], v[108:111], v[180:183], v[92:95]
	v_mfma_f32_16x16x32_bf16 v[88:91], v[132:135], v[180:183], v[88:91]
	v_mfma_f32_16x16x32_bf16 v[76:79], v[108:111], v[188:191], v[76:79]
	v_mfma_f32_16x16x32_bf16 v[72:75], v[132:135], v[188:191], v[72:75]
	s_setprio 0
	s_setprio 1
	v_mfma_f32_16x16x32_bf16 v[124:127], v[144:147], v[160:163], v[124:127]
	v_mfma_f32_16x16x32_bf16 v[120:123], v[152:155], v[160:163], v[120:123]
	v_mfma_f32_16x16x32_bf16 v[100:103], v[144:147], v[168:171], v[100:103]
	v_mfma_f32_16x16x32_bf16 v[96:99], v[152:155], v[168:171], v[96:99]
	v_mfma_f32_16x16x32_bf16 v[84:87], v[144:147], v[176:179], v[84:87]
	v_mfma_f32_16x16x32_bf16 v[80:83], v[152:155], v[176:179], v[80:83]
	v_mfma_f32_16x16x32_bf16 v[68:71], v[144:147], v[184:187], v[68:71]
	v_mfma_f32_16x16x32_bf16 v[64:67], v[152:155], v[184:187], v[64:67]
	v_mfma_f32_16x16x32_bf16 v[124:127], v[148:151], v[164:167], v[124:127]
	v_mfma_f32_16x16x32_bf16 v[120:123], v[156:159], v[164:167], v[120:123]
	v_mfma_f32_16x16x32_bf16 v[100:103], v[148:151], v[172:175], v[100:103]
	v_mfma_f32_16x16x32_bf16 v[96:99], v[156:159], v[172:175], v[96:99]
	v_mfma_f32_16x16x32_bf16 v[84:87], v[148:151], v[180:183], v[84:87]
	v_mfma_f32_16x16x32_bf16 v[80:83], v[156:159], v[180:183], v[80:83]
	v_mfma_f32_16x16x32_bf16 v[68:71], v[148:151], v[188:191], v[68:71]
	v_mfma_f32_16x16x32_bf16 v[64:67], v[156:159], v[188:191], v[64:67]
	s_setprio 0
	s_barrier
	s_add_i32 s26, s77, s3
	v_lshl_add_u64 v[204:205], v[204:205], 0, s[10:11]
	s_mov_b32 m0, s26
	ds_read_b128 v[160:163], v231 offset:49152
	ds_read_b128 v[164:167], v231 offset:50176
	ds_read_b128 v[168:171], v231 offset:51200
	ds_read_b128 v[172:175], v231 offset:52224
	ds_read_b128 v[176:179], v231 offset:53248
	ds_read_b128 v[180:183], v231 offset:54272
	ds_read_b128 v[184:187], v231 offset:55296
	ds_read_b128 v[188:191], v231 offset:56320
	global_load_lds_dwordx4 v[204:205], off
	s_add_i32 m0, s26, 0x2000
	s_add_u32 s26, s70, 0x40080
	v_lshl_add_u64 v[204:205], v[206:207], 0, s[10:11]
	s_addc_u32 s27, s71, 0
	s_add_i32 s70, s92, s3
	global_load_lds_dwordx4 v[204:205], off
	v_lshl_add_u64 v[204:205], s[26:27], 0, v[194:195]
	s_mov_b32 m0, s70
	s_nop 0
	global_load_lds_dwordx4 v[204:205], off
	v_lshl_add_u64 v[204:205], s[26:27], 0, v[198:199]
	s_add_i32 m0, s70, 0x2000
	s_nop 0
	global_load_lds_dwordx4 v[204:205], off
	v_lshl_add_u64 v[204:205], v[208:209], 0, s[10:11]
	s_mov_b32 m0, s81
	s_nop 0
	global_load_lds_dwordx4 v[204:205], off
	v_lshl_add_u64 v[204:205], v[210:211], 0, s[10:11]
	s_mov_b32 m0, s82
	s_nop 0
	global_load_lds_dwordx4 v[204:205], off
	s_waitcnt vmcnt(8)
	s_waitcnt lgkmcnt(0)
	s_barrier
	s_setprio 1
	s_waitcnt lgkmcnt(0)
	v_mfma_f32_16x16x32_bf16 v[60:63], v[104:107], v[160:163], v[60:63]
	v_mfma_f32_16x16x32_bf16 v[56:59], v[128:131], v[160:163], v[56:59]
	v_mfma_f32_16x16x32_bf16 v[44:47], v[104:107], v[168:171], v[44:47]
	v_mfma_f32_16x16x32_bf16 v[40:43], v[128:131], v[168:171], v[40:43]
	v_mfma_f32_16x16x32_bf16 v[28:31], v[104:107], v[176:179], v[28:31]
	v_mfma_f32_16x16x32_bf16 v[24:27], v[128:131], v[176:179], v[24:27]
	v_mfma_f32_16x16x32_bf16 v[12:15], v[104:107], v[184:187], v[12:15]
	v_mfma_f32_16x16x32_bf16 v[8:11], v[128:131], v[184:187], v[8:11]
	v_mfma_f32_16x16x32_bf16 v[60:63], v[108:111], v[164:167], v[60:63]
	v_mfma_f32_16x16x32_bf16 v[56:59], v[132:135], v[164:167], v[56:59]
	v_mfma_f32_16x16x32_bf16 v[44:47], v[108:111], v[172:175], v[44:47]
	v_mfma_f32_16x16x32_bf16 v[40:43], v[132:135], v[172:175], v[40:43]
	v_mfma_f32_16x16x32_bf16 v[28:31], v[108:111], v[180:183], v[28:31]
	v_mfma_f32_16x16x32_bf16 v[24:27], v[132:135], v[180:183], v[24:27]
	v_mfma_f32_16x16x32_bf16 v[12:15], v[108:111], v[188:191], v[12:15]
	v_mfma_f32_16x16x32_bf16 v[8:11], v[132:135], v[188:191], v[8:11]
	s_setprio 0
	s_setprio 1
	v_mfma_f32_16x16x32_bf16 v[52:55], v[144:147], v[160:163], v[52:55]
	v_mfma_f32_16x16x32_bf16 v[48:51], v[152:155], v[160:163], v[48:51]
	v_mfma_f32_16x16x32_bf16 v[36:39], v[144:147], v[168:171], v[36:39]
	v_mfma_f32_16x16x32_bf16 v[32:35], v[152:155], v[168:171], v[32:35]
	v_mfma_f32_16x16x32_bf16 v[20:23], v[144:147], v[176:179], v[20:23]
	v_mfma_f32_16x16x32_bf16 v[16:19], v[152:155], v[176:179], v[16:19]
	v_mfma_f32_16x16x32_bf16 v[4:7], v[144:147], v[184:187], v[4:7]
	v_mfma_f32_16x16x32_bf16 v[0:3], v[152:155], v[184:187], v[0:3]
	v_mfma_f32_16x16x32_bf16 v[52:55], v[148:151], v[164:167], v[52:55]
	v_mfma_f32_16x16x32_bf16 v[48:51], v[156:159], v[164:167], v[48:51]
	v_mfma_f32_16x16x32_bf16 v[36:39], v[148:151], v[172:175], v[36:39]
	v_mfma_f32_16x16x32_bf16 v[32:35], v[156:159], v[172:175], v[32:35]
	v_mfma_f32_16x16x32_bf16 v[20:23], v[148:151], v[180:183], v[20:23]
	v_mfma_f32_16x16x32_bf16 v[16:19], v[156:159], v[180:183], v[16:19]
	v_mfma_f32_16x16x32_bf16 v[4:7], v[148:151], v[188:191], v[4:7]
	v_mfma_f32_16x16x32_bf16 v[0:3], v[156:159], v[188:191], v[0:3]
	s_setprio 0
	s_barrier
	s_add_i32 s91, s91, 2
	s_add_u32 s5, s5, 0x100
	s_addc_u32 s61, s61, 0
	s_add_u32 s68, s68, 0x100
	s_addc_u32 s69, s69, 0

.LBB0_952:
	s_add_u32 s7, s10, 0x100
	s_addc_u32 s31, s11, 0
	s_add_u32 s8, s8, 0x40080
	v_mov_b32_e32 v2, 0
	s_addc_u32 s9, s9, 0
	s_mov_b32 s51, -2
	ds_read_b128 v[130:133], v167
	ds_read_b128 v[134:137], v167 offset:1024
	ds_read_b128 v[138:141], v167 offset:2048
	ds_read_b128 v[142:145], v167 offset:3072
	ds_read_b128 v[160:163], v168
	ds_read_b128 v[172:175], v168 offset:1024
	ds_read_b128 v[176:179], v168 offset:2048
	ds_read_b128 v[180:183], v168 offset:3072
	s_add_u32 s10, s8, 0xfffc0080
	s_addc_u32 s11, s9, -1
	s_cmp_eq_u32 s51, 12
	s_cselect_b32 s59, s53, s11
	s_cselect_b32 s58, s52, s10
	s_cselect_b32 s11, s57, s31
	s_cselect_b32 s10, s56, s7
	v_lshl_add_u64 v[164:165], s[8:9], 0, v[158:159]
	s_add_i32 m0, s84, 0xc000
	ds_read_b128 v[184:187], v169
	ds_read_b128 v[188:191], v169 offset:1024
	ds_read_b128 v[192:195], v169 offset:2048
	ds_read_b128 v[196:199], v169 offset:3072
	ds_read_b128 v[200:203], v169 offset:4096
	ds_read_b128 v[204:207], v169 offset:5120
	ds_read_b128 v[208:211], v169 offset:6144
	ds_read_b128 v[212:215], v169 offset:7168
	global_load_lds_dwordx4 v[164:165], off
	v_lshl_add_u64 v[164:165], s[8:9], 0, v[156:157]
	s_add_i32 m0, s84, 0xe000
	s_nop 0
	global_load_lds_dwordx4 v[164:165], off
	s_waitcnt vmcnt(8)
	s_waitcnt lgkmcnt(0)
	s_barrier
	s_setprio 1
	s_waitcnt lgkmcnt(0)
	v_mfma_f32_16x16x32_bf16 v[126:129], v[130:133], v[184:187], 0
	v_mfma_f32_16x16x32_bf16 v[122:125], v[138:141], v[184:187], 0
	v_mfma_f32_16x16x32_bf16 v[110:113], v[130:133], v[192:195], 0
	v_mfma_f32_16x16x32_bf16 v[106:109], v[138:141], v[192:195], 0
	v_mfma_f32_16x16x32_bf16 v[94:97], v[130:133], v[200:203], 0
	v_mfma_f32_16x16x32_bf16 v[90:93], v[138:141], v[200:203], 0
	v_mfma_f32_16x16x32_bf16 v[78:81], v[130:133], v[208:211], 0
	v_mfma_f32_16x16x32_bf16 v[74:77], v[138:141], v[208:211], 0
	v_mfma_f32_16x16x32_bf16 v[126:129], v[134:137], v[188:191], v[126:129]
	v_mfma_f32_16x16x32_bf16 v[122:125], v[142:145], v[188:191], v[122:125]
	v_mfma_f32_16x16x32_bf16 v[110:113], v[134:137], v[196:199], v[110:113]
	v_mfma_f32_16x16x32_bf16 v[106:109], v[142:145], v[196:199], v[106:109]
	v_mfma_f32_16x16x32_bf16 v[94:97], v[134:137], v[204:207], v[94:97]
	v_mfma_f32_16x16x32_bf16 v[90:93], v[142:145], v[204:207], v[90:93]
	v_mfma_f32_16x16x32_bf16 v[78:81], v[134:137], v[212:215], v[78:81]
	v_mfma_f32_16x16x32_bf16 v[74:77], v[142:145], v[212:215], v[74:77]
	s_setprio 0
	s_setprio 1
	v_mfma_f32_16x16x32_bf16 v[118:121], v[160:163], v[184:187], 0
	v_mfma_f32_16x16x32_bf16 v[114:117], v[176:179], v[184:187], 0
	v_mfma_f32_16x16x32_bf16 v[102:105], v[160:163], v[192:195], 0
	v_mfma_f32_16x16x32_bf16 v[98:101], v[176:179], v[192:195], 0
	v_mfma_f32_16x16x32_bf16 v[86:89], v[160:163], v[200:203], 0
	v_mfma_f32_16x16x32_bf16 v[82:85], v[176:179], v[200:203], 0
	v_mfma_f32_16x16x32_bf16 v[70:73], v[160:163], v[208:211], 0
	v_mfma_f32_16x16x32_bf16 v[66:69], v[176:179], v[208:211], 0
	v_mfma_f32_16x16x32_bf16 v[118:121], v[172:175], v[188:191], v[118:121]
	v_mfma_f32_16x16x32_bf16 v[114:117], v[180:183], v[188:191], v[114:117]
	v_mfma_f32_16x16x32_bf16 v[102:105], v[172:175], v[196:199], v[102:105]
	v_mfma_f32_16x16x32_bf16 v[98:101], v[180:183], v[196:199], v[98:101]
	v_mfma_f32_16x16x32_bf16 v[86:89], v[172:175], v[204:207], v[86:89]
	v_mfma_f32_16x16x32_bf16 v[82:85], v[180:183], v[204:207], v[82:85]
	v_mfma_f32_16x16x32_bf16 v[70:73], v[172:175], v[212:215], v[70:73]
	v_mfma_f32_16x16x32_bf16 v[66:69], v[180:183], v[212:215], v[66:69]
	s_setprio 0
	s_barrier
	s_add_i32 s26, s94, s39
	v_lshl_add_u64 v[164:165], s[10:11], 0, v[148:149]
	s_mov_b32 m0, s26
	ds_read_b128 v[184:187], v169 offset:16384
	ds_read_b128 v[188:191], v169 offset:17408
	ds_read_b128 v[192:195], v169 offset:18432
	ds_read_b128 v[196:199], v169 offset:19456
	ds_read_b128 v[200:203], v169 offset:20480
	ds_read_b128 v[204:207], v169 offset:21504
	ds_read_b128 v[208:211], v169 offset:22528
	ds_read_b128 v[212:215], v169 offset:23552
	global_load_lds_dwordx4 v[164:165], off
	s_add_i32 m0, s26, 0x2000
	s_add_u32 s26, s10, 0x40000
	v_lshl_add_u64 v[216:217], s[10:11], 0, v[152:153]
	s_addc_u32 s27, s11, 0
	s_add_i32 s60, s95, s39
	global_load_lds_dwordx4 v[216:217], off
	v_lshl_add_u64 v[218:219], s[26:27], 0, v[148:149]
	s_mov_b32 m0, s60
	v_lshl_add_u64 v[220:221], s[58:59], 0, v[150:151]
	global_load_lds_dwordx4 v[218:219], off
	v_lshl_add_u64 v[218:219], s[26:27], 0, v[152:153]
	s_add_i32 m0, s60, 0x2000
	s_nop 0
	global_load_lds_dwordx4 v[218:219], off
	v_lshl_add_u64 v[218:219], s[58:59], 0, v[146:147]
	s_mov_b32 m0, s84
	s_nop 0
	global_load_lds_dwordx4 v[218:219], off
	s_mov_b32 m0, s85
	s_nop 0
	global_load_lds_dwordx4 v[220:221], off
	s_waitcnt vmcnt(8)
	s_waitcnt lgkmcnt(0)
	s_barrier
	s_setprio 1
	s_waitcnt lgkmcnt(0)
	v_mfma_f32_16x16x32_bf16 v[62:65], v[130:133], v[184:187], 0
	v_mfma_f32_16x16x32_bf16 v[58:61], v[138:141], v[184:187], 0
	v_mfma_f32_16x16x32_bf16 v[46:49], v[130:133], v[192:195], 0
	v_mfma_f32_16x16x32_bf16 v[42:45], v[138:141], v[192:195], 0
	v_mfma_f32_16x16x32_bf16 v[30:33], v[130:133], v[200:203], 0
	v_mfma_f32_16x16x32_bf16 v[26:29], v[138:141], v[200:203], 0
	v_mfma_f32_16x16x32_bf16 v[14:17], v[130:133], v[208:211], 0
	v_mfma_f32_16x16x32_bf16 v[10:13], v[138:141], v[208:211], 0
	v_mfma_f32_16x16x32_bf16 v[62:65], v[134:137], v[188:191], v[62:65]
	v_mfma_f32_16x16x32_bf16 v[58:61], v[142:145], v[188:191], v[58:61]
	v_mfma_f32_16x16x32_bf16 v[46:49], v[134:137], v[196:199], v[46:49]
	v_mfma_f32_16x16x32_bf16 v[42:45], v[142:145], v[196:199], v[42:45]
	v_mfma_f32_16x16x32_bf16 v[30:33], v[134:137], v[204:207], v[30:33]
	v_mfma_f32_16x16x32_bf16 v[26:29], v[142:145], v[204:207], v[26:29]
	v_mfma_f32_16x16x32_bf16 v[14:17], v[134:137], v[212:215], v[14:17]
	v_mfma_f32_16x16x32_bf16 v[10:13], v[142:145], v[212:215], v[10:13]
	s_setprio 0
	s_setprio 1
	v_mfma_f32_16x16x32_bf16 v[54:57], v[160:163], v[184:187], 0
	v_mfma_f32_16x16x32_bf16 v[50:53], v[176:179], v[184:187], 0
	v_mfma_f32_16x16x32_bf16 v[38:41], v[160:163], v[192:195], 0
	v_mfma_f32_16x16x32_bf16 v[34:37], v[176:179], v[192:195], 0
	v_mfma_f32_16x16x32_bf16 v[22:25], v[160:163], v[200:203], 0
	v_mfma_f32_16x16x32_bf16 v[18:21], v[176:179], v[200:203], 0
	v_mfma_f32_16x16x32_bf16 v[6:9], v[160:163], v[208:211], 0
	v_mfma_f32_16x16x32_bf16 v[2:5], v[176:179], v[208:211], 0
	v_mfma_f32_16x16x32_bf16 v[54:57], v[172:175], v[188:191], v[54:57]
	v_mfma_f32_16x16x32_bf16 v[50:53], v[180:183], v[188:191], v[50:53]
	v_mfma_f32_16x16x32_bf16 v[38:41], v[172:175], v[196:199], v[38:41]
	v_mfma_f32_16x16x32_bf16 v[34:37], v[180:183], v[196:199], v[34:37]
	v_mfma_f32_16x16x32_bf16 v[22:25], v[172:175], v[204:207], v[22:25]
	v_mfma_f32_16x16x32_bf16 v[18:21], v[180:183], v[204:207], v[18:21]
	v_mfma_f32_16x16x32_bf16 v[6:9], v[172:175], v[212:215], v[6:9]
	v_mfma_f32_16x16x32_bf16 v[2:5], v[180:183], v[212:215], v[2:5]
	s_setprio 0
	s_barrier
	s_add_i32 s60, 0, 0x18000
	v_add_u32_e32 v1, s60, v166
	s_add_i32 s61, 0, 0x1c000
	ds_read_b128 v[130:133], v1
	ds_read_b128 v[134:137], v1 offset:1024
	ds_read_b128 v[138:141], v1 offset:2048
	ds_read_b128 v[142:145], v1 offset:3072
	v_add_u32_e32 v1, s61, v166
	ds_read_b128 v[160:163], v1
	ds_read_b128 v[172:175], v1 offset:1024
	ds_read_b128 v[176:179], v1 offset:2048
	ds_read_b128 v[180:183], v1 offset:3072
	s_add_u32 s26, s58, 0x40000
	s_addc_u32 s27, s59, 0
	s_mov_b32 m0, s86
	v_lshl_add_u64 v[222:223], s[26:27], 0, v[146:147]
	ds_read_b128 v[184:187], v169 offset:32768
	ds_read_b128 v[188:191], v169 offset:33792
	ds_read_b128 v[192:195], v169 offset:34816
	ds_read_b128 v[196:199], v169 offset:35840
	ds_read_b128 v[200:203], v169 offset:36864
	ds_read_b128 v[204:207], v169 offset:37888
	ds_read_b128 v[208:211], v169 offset:38912
	ds_read_b128 v[212:215], v169 offset:39936
	global_load_lds_dwordx4 v[222:223], off
	v_lshl_add_u64 v[222:223], s[26:27], 0, v[150:151]
	s_mov_b32 m0, s87
	s_nop 0
	global_load_lds_dwordx4 v[222:223], off
	s_waitcnt vmcnt(8)
	s_waitcnt lgkmcnt(0)
	s_barrier
	s_setprio 1
	s_waitcnt lgkmcnt(0)
	v_mfma_f32_16x16x32_bf16 v[126:129], v[130:133], v[184:187], v[126:129]
	v_mfma_f32_16x16x32_bf16 v[122:125], v[138:141], v[184:187], v[122:125]
	v_mfma_f32_16x16x32_bf16 v[110:113], v[130:133], v[192:195], v[110:113]
	v_mfma_f32_16x16x32_bf16 v[106:109], v[138:141], v[192:195], v[106:109]
	v_mfma_f32_16x16x32_bf16 v[94:97], v[130:133], v[200:203], v[94:97]
	v_mfma_f32_16x16x32_bf16 v[90:93], v[138:141], v[200:203], v[90:93]
	v_mfma_f32_16x16x32_bf16 v[78:81], v[130:133], v[208:211], v[78:81]
	v_mfma_f32_16x16x32_bf16 v[74:77], v[138:141], v[208:211], v[74:77]
	v_mfma_f32_16x16x32_bf16 v[126:129], v[134:137], v[188:191], v[126:129]
	v_mfma_f32_16x16x32_bf16 v[122:125], v[142:145], v[188:191], v[122:125]
	v_mfma_f32_16x16x32_bf16 v[110:113], v[134:137], v[196:199], v[110:113]
	v_mfma_f32_16x16x32_bf16 v[106:109], v[142:145], v[196:199], v[106:109]
	v_mfma_f32_16x16x32_bf16 v[94:97], v[134:137], v[204:207], v[94:97]
	v_mfma_f32_16x16x32_bf16 v[90:93], v[142:145], v[204:207], v[90:93]
	v_mfma_f32_16x16x32_bf16 v[78:81], v[134:137], v[212:215], v[78:81]
	v_mfma_f32_16x16x32_bf16 v[74:77], v[142:145], v[212:215], v[74:77]
	s_setprio 0
	s_setprio 1
	v_mfma_f32_16x16x32_bf16 v[118:121], v[160:163], v[184:187], v[118:121]
	v_mfma_f32_16x16x32_bf16 v[114:117], v[176:179], v[184:187], v[114:117]
	v_mfma_f32_16x16x32_bf16 v[102:105], v[160:163], v[192:195], v[102:105]
	v_mfma_f32_16x16x32_bf16 v[98:101], v[176:179], v[192:195], v[98:101]
	v_mfma_f32_16x16x32_bf16 v[86:89], v[160:163], v[200:203], v[86:89]
	v_mfma_f32_16x16x32_bf16 v[82:85], v[176:179], v[200:203], v[82:85]
	v_mfma_f32_16x16x32_bf16 v[70:73], v[160:163], v[208:211], v[70:73]
	v_mfma_f32_16x16x32_bf16 v[66:69], v[176:179], v[208:211], v[66:69]
	v_mfma_f32_16x16x32_bf16 v[118:121], v[172:175], v[188:191], v[118:121]
	v_mfma_f32_16x16x32_bf16 v[114:117], v[180:183], v[188:191], v[114:117]
	v_mfma_f32_16x16x32_bf16 v[102:105], v[172:175], v[196:199], v[102:105]
	v_mfma_f32_16x16x32_bf16 v[98:101], v[180:183], v[196:199], v[98:101]
	v_mfma_f32_16x16x32_bf16 v[86:89], v[172:175], v[204:207], v[86:89]
	v_mfma_f32_16x16x32_bf16 v[82:85], v[180:183], v[204:207], v[82:85]
	v_mfma_f32_16x16x32_bf16 v[70:73], v[172:175], v[212:215], v[70:73]
	v_mfma_f32_16x16x32_bf16 v[66:69], v[180:183], v[212:215], v[66:69]
	s_setprio 0
	s_barrier
	s_add_i32 s26, s60, s39
	v_lshl_add_u64 v[164:165], v[164:165], 0, s[18:19]
	s_mov_b32 m0, s26
	ds_read_b128 v[184:187], v169 offset:49152
	ds_read_b128 v[188:191], v169 offset:50176
	ds_read_b128 v[192:195], v169 offset:51200
	ds_read_b128 v[196:199], v169 offset:52224
	ds_read_b128 v[200:203], v169 offset:53248
	ds_read_b128 v[204:207], v169 offset:54272
	ds_read_b128 v[208:211], v169 offset:55296
	ds_read_b128 v[212:215], v169 offset:56320
	global_load_lds_dwordx4 v[164:165], off
	s_add_i32 m0, s26, 0x2000
	s_add_u32 s10, s10, 0x40080
	v_lshl_add_u64 v[164:165], v[216:217], 0, s[18:19]
	s_addc_u32 s11, s11, 0
	s_add_i32 s26, s61, s39
	global_load_lds_dwordx4 v[164:165], off
	v_lshl_add_u64 v[164:165], s[10:11], 0, v[148:149]
	s_mov_b32 m0, s26
	s_nop 0
	global_load_lds_dwordx4 v[164:165], off
	v_lshl_add_u64 v[164:165], s[10:11], 0, v[152:153]
	s_add_i32 m0, s26, 0x2000
	s_nop 0
	global_load_lds_dwordx4 v[164:165], off
	v_lshl_add_u64 v[164:165], v[218:219], 0, s[18:19]
	s_mov_b32 m0, s91
	s_nop 0
	global_load_lds_dwordx4 v[164:165], off
	v_lshl_add_u64 v[164:165], v[220:221], 0, s[18:19]
	s_mov_b32 m0, s92
	s_nop 0
	global_load_lds_dwordx4 v[164:165], off
	s_waitcnt vmcnt(8)
	s_waitcnt lgkmcnt(0)
	s_barrier
	s_setprio 1
	s_waitcnt lgkmcnt(0)
	v_mfma_f32_16x16x32_bf16 v[62:65], v[130:133], v[184:187], v[62:65]
	v_mfma_f32_16x16x32_bf16 v[58:61], v[138:141], v[184:187], v[58:61]
	v_mfma_f32_16x16x32_bf16 v[46:49], v[130:133], v[192:195], v[46:49]
	v_mfma_f32_16x16x32_bf16 v[42:45], v[138:141], v[192:195], v[42:45]
	v_mfma_f32_16x16x32_bf16 v[30:33], v[130:133], v[200:203], v[30:33]
	v_mfma_f32_16x16x32_bf16 v[26:29], v[138:141], v[200:203], v[26:29]
	v_mfma_f32_16x16x32_bf16 v[14:17], v[130:133], v[208:211], v[14:17]
	v_mfma_f32_16x16x32_bf16 v[10:13], v[138:141], v[208:211], v[10:13]
	v_mfma_f32_16x16x32_bf16 v[62:65], v[134:137], v[188:191], v[62:65]
	v_mfma_f32_16x16x32_bf16 v[58:61], v[142:145], v[188:191], v[58:61]
	v_mfma_f32_16x16x32_bf16 v[46:49], v[134:137], v[196:199], v[46:49]
	v_mfma_f32_16x16x32_bf16 v[42:45], v[142:145], v[196:199], v[42:45]
	v_mfma_f32_16x16x32_bf16 v[30:33], v[134:137], v[204:207], v[30:33]
	v_mfma_f32_16x16x32_bf16 v[26:29], v[142:145], v[204:207], v[26:29]
	v_mfma_f32_16x16x32_bf16 v[14:17], v[134:137], v[212:215], v[14:17]
	v_mfma_f32_16x16x32_bf16 v[10:13], v[142:145], v[212:215], v[10:13]
	s_setprio 0
	s_setprio 1
	v_mfma_f32_16x16x32_bf16 v[54:57], v[160:163], v[184:187], v[54:57]
	v_mfma_f32_16x16x32_bf16 v[50:53], v[176:179], v[184:187], v[50:53]
	v_mfma_f32_16x16x32_bf16 v[38:41], v[160:163], v[192:195], v[38:41]
	v_mfma_f32_16x16x32_bf16 v[34:37], v[176:179], v[192:195], v[34:37]
	v_mfma_f32_16x16x32_bf16 v[22:25], v[160:163], v[200:203], v[22:25]
	v_mfma_f32_16x16x32_bf16 v[18:21], v[176:179], v[200:203], v[18:21]
	v_mfma_f32_16x16x32_bf16 v[6:9], v[160:163], v[208:211], v[6:9]
	v_mfma_f32_16x16x32_bf16 v[2:5], v[176:179], v[208:211], v[2:5]
	v_mfma_f32_16x16x32_bf16 v[54:57], v[172:175], v[188:191], v[54:57]
	v_mfma_f32_16x16x32_bf16 v[50:53], v[180:183], v[188:191], v[50:53]
	v_mfma_f32_16x16x32_bf16 v[38:41], v[172:175], v[196:199], v[38:41]
	v_mfma_f32_16x16x32_bf16 v[34:37], v[180:183], v[196:199], v[34:37]
	v_mfma_f32_16x16x32_bf16 v[22:25], v[172:175], v[204:207], v[22:25]
	v_mfma_f32_16x16x32_bf16 v[18:21], v[180:183], v[204:207], v[18:21]
	v_mfma_f32_16x16x32_bf16 v[6:9], v[172:175], v[212:215], v[6:9]
	v_mfma_f32_16x16x32_bf16 v[2:5], v[180:183], v[212:215], v[2:5]
	s_setprio 0
	s_barrier
	s_add_i32 s51, s51, 2
	s_add_u32 s7, s7, 0x100
	s_addc_u32 s31, s31, 0
	s_add_u32 s8, s8, 0x100
	s_addc_u32 s9, s9, 0

.LBB0_1518:
	s_add_u32 s23, s6, 0x100
	s_addc_u32 s60, s7, 0
	s_add_u32 s4, s4, 0x40080
	v_mov_b32_e32 v0, 0
	s_addc_u32 s5, s5, 0
	s_mov_b32 s61, -2
	ds_read_b128 v[128:131], v246
	ds_read_b128 v[132:135], v246 offset:1024
	ds_read_b128 v[136:139], v246 offset:2048
	ds_read_b128 v[140:143], v246 offset:3072
	ds_read_b128 v[144:147], v247
	ds_read_b128 v[148:151], v247 offset:1024
	ds_read_b128 v[152:155], v247 offset:2048
	ds_read_b128 v[156:159], v247 offset:3072
	s_add_u32 s6, s4, 0xfffc0080
	s_addc_u32 s7, s5, -1
	s_cmp_eq_u32 s61, 12
	s_cselect_b32 s35, s25, s7
	s_cselect_b32 s34, s24, s6
	s_cselect_b32 s7, s27, s60
	s_cselect_b32 s6, s26, s23
	v_lshl_add_u64 v[192:193], s[4:5], 0, v[218:219]
	s_add_i32 m0, s36, 0xc000
	ds_read_b128 v[160:163], v248
	ds_read_b128 v[164:167], v248 offset:1024
	ds_read_b128 v[168:171], v248 offset:2048
	ds_read_b128 v[172:175], v248 offset:3072
	ds_read_b128 v[176:179], v248 offset:4096
	ds_read_b128 v[180:183], v248 offset:5120
	ds_read_b128 v[184:187], v248 offset:6144
	ds_read_b128 v[188:191], v248 offset:7168
	global_load_lds_dwordx4 v[192:193], off
	v_lshl_add_u64 v[192:193], s[4:5], 0, v[216:217]
	s_add_i32 m0, s36, 0xe000
	s_nop 0
	global_load_lds_dwordx4 v[192:193], off
	s_waitcnt vmcnt(8)
	s_waitcnt lgkmcnt(0)
	s_barrier
	s_setprio 1
	s_waitcnt lgkmcnt(0)
	v_mfma_f32_16x16x32_bf16 v[124:127], v[128:131], v[160:163], 0
	v_mfma_f32_16x16x32_bf16 v[120:123], v[136:139], v[160:163], 0
	v_mfma_f32_16x16x32_bf16 v[112:115], v[128:131], v[168:171], 0
	v_mfma_f32_16x16x32_bf16 v[104:107], v[136:139], v[168:171], 0
	v_mfma_f32_16x16x32_bf16 v[96:99], v[128:131], v[176:179], 0
	v_mfma_f32_16x16x32_bf16 v[88:91], v[136:139], v[176:179], 0
	v_mfma_f32_16x16x32_bf16 v[80:83], v[128:131], v[184:187], 0
	v_mfma_f32_16x16x32_bf16 v[72:75], v[136:139], v[184:187], 0
	v_mfma_f32_16x16x32_bf16 v[124:127], v[132:135], v[164:167], v[124:127]
	v_mfma_f32_16x16x32_bf16 v[120:123], v[140:143], v[164:167], v[120:123]
	v_mfma_f32_16x16x32_bf16 v[112:115], v[132:135], v[172:175], v[112:115]
	v_mfma_f32_16x16x32_bf16 v[104:107], v[140:143], v[172:175], v[104:107]
	v_mfma_f32_16x16x32_bf16 v[96:99], v[132:135], v[180:183], v[96:99]
	v_mfma_f32_16x16x32_bf16 v[88:91], v[140:143], v[180:183], v[88:91]
	v_mfma_f32_16x16x32_bf16 v[80:83], v[132:135], v[188:191], v[80:83]
	v_mfma_f32_16x16x32_bf16 v[72:75], v[140:143], v[188:191], v[72:75]
	s_setprio 0
	s_setprio 1
	v_mfma_f32_16x16x32_bf16 v[116:119], v[144:147], v[160:163], 0
	v_mfma_f32_16x16x32_bf16 v[108:111], v[152:155], v[160:163], 0
	v_mfma_f32_16x16x32_bf16 v[100:103], v[144:147], v[168:171], 0
	v_mfma_f32_16x16x32_bf16 v[92:95], v[152:155], v[168:171], 0
	v_mfma_f32_16x16x32_bf16 v[84:87], v[144:147], v[176:179], 0
	v_mfma_f32_16x16x32_bf16 v[76:79], v[152:155], v[176:179], 0
	v_mfma_f32_16x16x32_bf16 v[68:71], v[144:147], v[184:187], 0
	v_mfma_f32_16x16x32_bf16 v[64:67], v[152:155], v[184:187], 0
	v_mfma_f32_16x16x32_bf16 v[116:119], v[148:151], v[164:167], v[116:119]
	v_mfma_f32_16x16x32_bf16 v[108:111], v[156:159], v[164:167], v[108:111]
	v_mfma_f32_16x16x32_bf16 v[100:103], v[148:151], v[172:175], v[100:103]
	v_mfma_f32_16x16x32_bf16 v[92:95], v[156:159], v[172:175], v[92:95]
	v_mfma_f32_16x16x32_bf16 v[84:87], v[148:151], v[180:183], v[84:87]
	v_mfma_f32_16x16x32_bf16 v[76:79], v[156:159], v[180:183], v[76:79]
	v_mfma_f32_16x16x32_bf16 v[68:71], v[148:151], v[188:191], v[68:71]
	v_mfma_f32_16x16x32_bf16 v[64:67], v[156:159], v[188:191], v[64:67]
	s_setprio 0
	s_barrier
	s_add_i32 s62, s48, s3
	v_lshl_add_u64 v[192:193], s[6:7], 0, v[212:213]
	s_mov_b32 m0, s62
	ds_read_b128 v[160:163], v248 offset:16384
	ds_read_b128 v[164:167], v248 offset:17408
	ds_read_b128 v[168:171], v248 offset:18432
	ds_read_b128 v[172:175], v248 offset:19456
	ds_read_b128 v[176:179], v248 offset:20480
	ds_read_b128 v[180:183], v248 offset:21504
	ds_read_b128 v[184:187], v248 offset:22528
	ds_read_b128 v[188:191], v248 offset:23552
	global_load_lds_dwordx4 v[192:193], off
	s_add_i32 m0, s62, 0x2000
	s_add_u32 s62, s6, 0x40000
	v_lshl_add_u64 v[194:195], s[6:7], 0, v[208:209]
	s_addc_u32 s63, s7, 0
	s_add_i32 s64, s49, s3
	global_load_lds_dwordx4 v[194:195], off
	v_lshl_add_u64 v[196:197], s[62:63], 0, v[212:213]
	s_mov_b32 m0, s64
	v_lshl_add_u64 v[198:199], s[34:35], 0, v[210:211]
	global_load_lds_dwordx4 v[196:197], off
	v_lshl_add_u64 v[196:197], s[62:63], 0, v[208:209]
	s_add_i32 m0, s64, 0x2000
	s_nop 0
	global_load_lds_dwordx4 v[196:197], off
	v_lshl_add_u64 v[196:197], s[34:35], 0, v[214:215]
	s_mov_b32 m0, s36
	s_nop 0
	global_load_lds_dwordx4 v[196:197], off
	s_mov_b32 m0, s37
	s_nop 0
	global_load_lds_dwordx4 v[198:199], off
	s_waitcnt vmcnt(8)
	s_waitcnt lgkmcnt(0)
	s_barrier
	s_setprio 1
	s_waitcnt lgkmcnt(0)
	v_mfma_f32_16x16x32_bf16 v[60:63], v[128:131], v[160:163], 0
	v_mfma_f32_16x16x32_bf16 v[56:59], v[136:139], v[160:163], 0
	v_mfma_f32_16x16x32_bf16 v[48:51], v[128:131], v[168:171], 0
	v_mfma_f32_16x16x32_bf16 v[40:43], v[136:139], v[168:171], 0
	v_mfma_f32_16x16x32_bf16 v[32:35], v[128:131], v[176:179], 0
	v_mfma_f32_16x16x32_bf16 v[24:27], v[136:139], v[176:179], 0
	v_mfma_f32_16x16x32_bf16 v[16:19], v[128:131], v[184:187], 0
	v_mfma_f32_16x16x32_bf16 v[8:11], v[136:139], v[184:187], 0
	v_mfma_f32_16x16x32_bf16 v[60:63], v[132:135], v[164:167], v[60:63]
	v_mfma_f32_16x16x32_bf16 v[56:59], v[140:143], v[164:167], v[56:59]
	v_mfma_f32_16x16x32_bf16 v[48:51], v[132:135], v[172:175], v[48:51]
	v_mfma_f32_16x16x32_bf16 v[40:43], v[140:143], v[172:175], v[40:43]
	v_mfma_f32_16x16x32_bf16 v[32:35], v[132:135], v[180:183], v[32:35]
	v_mfma_f32_16x16x32_bf16 v[24:27], v[140:143], v[180:183], v[24:27]
	v_mfma_f32_16x16x32_bf16 v[16:19], v[132:135], v[188:191], v[16:19]
	v_mfma_f32_16x16x32_bf16 v[8:11], v[140:143], v[188:191], v[8:11]
	s_setprio 0
	s_setprio 1
	v_mfma_f32_16x16x32_bf16 v[52:55], v[144:147], v[160:163], 0
	v_mfma_f32_16x16x32_bf16 v[44:47], v[152:155], v[160:163], 0
	v_mfma_f32_16x16x32_bf16 v[36:39], v[144:147], v[168:171], 0
	v_mfma_f32_16x16x32_bf16 v[28:31], v[152:155], v[168:171], 0
	v_mfma_f32_16x16x32_bf16 v[20:23], v[144:147], v[176:179], 0
	v_mfma_f32_16x16x32_bf16 v[12:15], v[152:155], v[176:179], 0
	v_mfma_f32_16x16x32_bf16 v[4:7], v[144:147], v[184:187], 0
	v_mfma_f32_16x16x32_bf16 v[0:3], v[152:155], v[184:187], 0
	v_mfma_f32_16x16x32_bf16 v[52:55], v[148:151], v[164:167], v[52:55]
	v_mfma_f32_16x16x32_bf16 v[44:47], v[156:159], v[164:167], v[44:47]
	v_mfma_f32_16x16x32_bf16 v[36:39], v[148:151], v[172:175], v[36:39]
	v_mfma_f32_16x16x32_bf16 v[28:31], v[156:159], v[172:175], v[28:31]
	v_mfma_f32_16x16x32_bf16 v[20:23], v[148:151], v[180:183], v[20:23]
	v_mfma_f32_16x16x32_bf16 v[12:15], v[156:159], v[180:183], v[12:15]
	v_mfma_f32_16x16x32_bf16 v[4:7], v[148:151], v[188:191], v[4:7]
	v_mfma_f32_16x16x32_bf16 v[0:3], v[156:159], v[188:191], v[0:3]
	s_setprio 0
	s_barrier
	s_add_i32 s62, 0, 0x18000
	s_add_i32 s63, 0, 0x1c000
	v_add_u32_e32 v140, s62, v245
	v_add_u32_e32 v156, s63, v245
	ds_read_b128 v[128:131], v140
	ds_read_b128 v[132:135], v140 offset:1024
	ds_read_b128 v[136:139], v140 offset:2048
	ds_read_b128 v[140:143], v140 offset:3072
	ds_read_b128 v[144:147], v156
	ds_read_b128 v[148:151], v156 offset:1024
	ds_read_b128 v[152:155], v156 offset:2048
	ds_read_b128 v[156:159], v156 offset:3072
	s_add_u32 s34, s34, 0x40000
	s_addc_u32 s35, s35, 0
	s_mov_b32 m0, s38
	v_lshl_add_u64 v[200:201], s[34:35], 0, v[214:215]
	ds_read_b128 v[160:163], v248 offset:32768
	ds_read_b128 v[164:167], v248 offset:33792
	ds_read_b128 v[168:171], v248 offset:34816
	ds_read_b128 v[172:175], v248 offset:35840
	ds_read_b128 v[176:179], v248 offset:36864
	ds_read_b128 v[180:183], v248 offset:37888
	ds_read_b128 v[184:187], v248 offset:38912
	ds_read_b128 v[188:191], v248 offset:39936
	global_load_lds_dwordx4 v[200:201], off
	v_lshl_add_u64 v[200:201], s[34:35], 0, v[210:211]
	s_mov_b32 m0, s39
	s_nop 0
	global_load_lds_dwordx4 v[200:201], off
	s_waitcnt vmcnt(8)
	s_waitcnt lgkmcnt(0)
	s_barrier
	s_setprio 1
	s_waitcnt lgkmcnt(0)
	v_mfma_f32_16x16x32_bf16 v[124:127], v[128:131], v[160:163], v[124:127]
	v_mfma_f32_16x16x32_bf16 v[120:123], v[136:139], v[160:163], v[120:123]
	v_mfma_f32_16x16x32_bf16 v[112:115], v[128:131], v[168:171], v[112:115]
	v_mfma_f32_16x16x32_bf16 v[104:107], v[136:139], v[168:171], v[104:107]
	v_mfma_f32_16x16x32_bf16 v[96:99], v[128:131], v[176:179], v[96:99]
	v_mfma_f32_16x16x32_bf16 v[88:91], v[136:139], v[176:179], v[88:91]
	v_mfma_f32_16x16x32_bf16 v[80:83], v[128:131], v[184:187], v[80:83]
	v_mfma_f32_16x16x32_bf16 v[72:75], v[136:139], v[184:187], v[72:75]
	v_mfma_f32_16x16x32_bf16 v[124:127], v[132:135], v[164:167], v[124:127]
	v_mfma_f32_16x16x32_bf16 v[120:123], v[140:143], v[164:167], v[120:123]
	v_mfma_f32_16x16x32_bf16 v[112:115], v[132:135], v[172:175], v[112:115]
	v_mfma_f32_16x16x32_bf16 v[104:107], v[140:143], v[172:175], v[104:107]
	v_mfma_f32_16x16x32_bf16 v[96:99], v[132:135], v[180:183], v[96:99]
	v_mfma_f32_16x16x32_bf16 v[88:91], v[140:143], v[180:183], v[88:91]
	v_mfma_f32_16x16x32_bf16 v[80:83], v[132:135], v[188:191], v[80:83]
	v_mfma_f32_16x16x32_bf16 v[72:75], v[140:143], v[188:191], v[72:75]
	s_setprio 0
	s_setprio 1
	v_mfma_f32_16x16x32_bf16 v[116:119], v[144:147], v[160:163], v[116:119]
	v_mfma_f32_16x16x32_bf16 v[108:111], v[152:155], v[160:163], v[108:111]
	v_mfma_f32_16x16x32_bf16 v[100:103], v[144:147], v[168:171], v[100:103]
	v_mfma_f32_16x16x32_bf16 v[92:95], v[152:155], v[168:171], v[92:95]
	v_mfma_f32_16x16x32_bf16 v[84:87], v[144:147], v[176:179], v[84:87]
	v_mfma_f32_16x16x32_bf16 v[76:79], v[152:155], v[176:179], v[76:79]
	v_mfma_f32_16x16x32_bf16 v[68:71], v[144:147], v[184:187], v[68:71]
	v_mfma_f32_16x16x32_bf16 v[64:67], v[152:155], v[184:187], v[64:67]
	v_mfma_f32_16x16x32_bf16 v[116:119], v[148:151], v[164:167], v[116:119]
	v_mfma_f32_16x16x32_bf16 v[108:111], v[156:159], v[164:167], v[108:111]
	v_mfma_f32_16x16x32_bf16 v[100:103], v[148:151], v[172:175], v[100:103]
	v_mfma_f32_16x16x32_bf16 v[92:95], v[156:159], v[172:175], v[92:95]
	v_mfma_f32_16x16x32_bf16 v[84:87], v[148:151], v[180:183], v[84:87]
	v_mfma_f32_16x16x32_bf16 v[76:79], v[156:159], v[180:183], v[76:79]
	v_mfma_f32_16x16x32_bf16 v[68:71], v[148:151], v[188:191], v[68:71]
	v_mfma_f32_16x16x32_bf16 v[64:67], v[156:159], v[188:191], v[64:67]
	s_setprio 0
	s_barrier
	s_add_i32 s34, s62, s3
	v_lshl_add_u64 v[192:193], v[192:193], 0, s[10:11]
	s_mov_b32 m0, s34
	ds_read_b128 v[160:163], v248 offset:49152
	ds_read_b128 v[164:167], v248 offset:50176
	ds_read_b128 v[168:171], v248 offset:51200
	ds_read_b128 v[172:175], v248 offset:52224
	ds_read_b128 v[176:179], v248 offset:53248
	ds_read_b128 v[180:183], v248 offset:54272
	ds_read_b128 v[184:187], v248 offset:55296
	ds_read_b128 v[188:191], v248 offset:56320
	global_load_lds_dwordx4 v[192:193], off
	s_add_i32 m0, s34, 0x2000
	s_add_u32 s6, s6, 0x40080
	v_lshl_add_u64 v[192:193], v[194:195], 0, s[10:11]
	s_addc_u32 s7, s7, 0
	s_add_i32 s34, s63, s3
	global_load_lds_dwordx4 v[192:193], off
	v_lshl_add_u64 v[192:193], s[6:7], 0, v[212:213]
	s_mov_b32 m0, s34
	s_nop 0
	global_load_lds_dwordx4 v[192:193], off
	v_lshl_add_u64 v[192:193], s[6:7], 0, v[208:209]
	s_add_i32 m0, s34, 0x2000
	s_nop 0
	global_load_lds_dwordx4 v[192:193], off
	v_lshl_add_u64 v[192:193], v[196:197], 0, s[10:11]
	s_mov_b32 m0, s44
	s_nop 0
	global_load_lds_dwordx4 v[192:193], off
	v_lshl_add_u64 v[192:193], v[198:199], 0, s[10:11]
	s_mov_b32 m0, s45
	s_nop 0
	global_load_lds_dwordx4 v[192:193], off
	s_waitcnt vmcnt(8)
	s_waitcnt lgkmcnt(0)
	s_barrier
	s_setprio 1
	s_waitcnt lgkmcnt(0)
	v_mfma_f32_16x16x32_bf16 v[60:63], v[128:131], v[160:163], v[60:63]
	v_mfma_f32_16x16x32_bf16 v[56:59], v[136:139], v[160:163], v[56:59]
	v_mfma_f32_16x16x32_bf16 v[48:51], v[128:131], v[168:171], v[48:51]
	v_mfma_f32_16x16x32_bf16 v[40:43], v[136:139], v[168:171], v[40:43]
	v_mfma_f32_16x16x32_bf16 v[32:35], v[128:131], v[176:179], v[32:35]
	v_mfma_f32_16x16x32_bf16 v[24:27], v[136:139], v[176:179], v[24:27]
	v_mfma_f32_16x16x32_bf16 v[16:19], v[128:131], v[184:187], v[16:19]
	v_mfma_f32_16x16x32_bf16 v[8:11], v[136:139], v[184:187], v[8:11]
	v_mfma_f32_16x16x32_bf16 v[60:63], v[132:135], v[164:167], v[60:63]
	v_mfma_f32_16x16x32_bf16 v[56:59], v[140:143], v[164:167], v[56:59]
	v_mfma_f32_16x16x32_bf16 v[48:51], v[132:135], v[172:175], v[48:51]
	v_mfma_f32_16x16x32_bf16 v[40:43], v[140:143], v[172:175], v[40:43]
	v_mfma_f32_16x16x32_bf16 v[32:35], v[132:135], v[180:183], v[32:35]
	v_mfma_f32_16x16x32_bf16 v[24:27], v[140:143], v[180:183], v[24:27]
	v_mfma_f32_16x16x32_bf16 v[16:19], v[132:135], v[188:191], v[16:19]
	v_mfma_f32_16x16x32_bf16 v[8:11], v[140:143], v[188:191], v[8:11]
	s_setprio 0
	s_setprio 1
	v_mfma_f32_16x16x32_bf16 v[52:55], v[144:147], v[160:163], v[52:55]
	v_mfma_f32_16x16x32_bf16 v[44:47], v[152:155], v[160:163], v[44:47]
	v_mfma_f32_16x16x32_bf16 v[36:39], v[144:147], v[168:171], v[36:39]
	v_mfma_f32_16x16x32_bf16 v[28:31], v[152:155], v[168:171], v[28:31]
	v_mfma_f32_16x16x32_bf16 v[20:23], v[144:147], v[176:179], v[20:23]
	v_mfma_f32_16x16x32_bf16 v[12:15], v[152:155], v[176:179], v[12:15]
	v_mfma_f32_16x16x32_bf16 v[4:7], v[144:147], v[184:187], v[4:7]
	v_mfma_f32_16x16x32_bf16 v[0:3], v[152:155], v[184:187], v[0:3]
	v_mfma_f32_16x16x32_bf16 v[52:55], v[148:151], v[164:167], v[52:55]
	v_mfma_f32_16x16x32_bf16 v[44:47], v[156:159], v[164:167], v[44:47]
	v_mfma_f32_16x16x32_bf16 v[36:39], v[148:151], v[172:175], v[36:39]
	v_mfma_f32_16x16x32_bf16 v[28:31], v[156:159], v[172:175], v[28:31]
	v_mfma_f32_16x16x32_bf16 v[20:23], v[148:151], v[180:183], v[20:23]
	v_mfma_f32_16x16x32_bf16 v[12:15], v[156:159], v[180:183], v[12:15]
	v_mfma_f32_16x16x32_bf16 v[4:7], v[148:151], v[188:191], v[4:7]
	v_mfma_f32_16x16x32_bf16 v[0:3], v[156:159], v[188:191], v[0:3]
	s_setprio 0
	s_barrier
	s_add_i32 s61, s61, 2
	s_add_u32 s23, s23, 0x100
	s_addc_u32 s60, s60, 0
	s_add_u32 s4, s4, 0x100
	s_addc_u32 s5, s5, 0
